# conv stage row loads scalarised: wave-uniform row address in an SGPR pair (saddr form), one scalar range test per round instead of per-row VALU compares, zero fill and exec masking
# speedup vs baseline: 1.0062x; 1.0062x over previous
.LBB0_653:
	v_or_b32_e32 v96, s47, v166
	v_subrev_u32_e32 v250, s28, v100
	v_readfirstlane_b32 s48, v96
	s_nop 0
	s_add_i32 s48, s48, s46
	s_add_i32 s49, s48, 11
	s_cmp_ge_i32 s48, s44
	s_cbranch_scc0 .Lcs3_slow
	s_cmp_lt_i32 s49, s45
	s_cbranch_scc0 .Lcs3_slow
	s_lshl_b32 s49, s48, 12
	s_add_u32 s98, s28, s49
	s_addc_u32 s99, s29, 0
	global_load_dwordx4 v[52:55], v250, s[98:99]
	s_add_u32 s98, s98, 0x1000
	s_addc_u32 s99, s99, 0
	global_load_dwordx4 v[48:51], v250, s[98:99]
	s_add_u32 s98, s98, 0x1000
	s_addc_u32 s99, s99, 0
	global_load_dwordx4 v[60:63], v250, s[98:99]
	s_add_u32 s98, s98, 0x1000
	s_addc_u32 s99, s99, 0
	global_load_dwordx4 v[56:59], v250, s[98:99]
	s_add_u32 s98, s98, 0x1000
	s_addc_u32 s99, s99, 0
	global_load_dwordx4 v[68:71], v250, s[98:99]
	s_add_u32 s98, s98, 0x1000
	s_addc_u32 s99, s99, 0
	global_load_dwordx4 v[64:67], v250, s[98:99]
	s_add_u32 s98, s98, 0x1000
	s_addc_u32 s99, s99, 0
	global_load_dwordx4 v[76:79], v250, s[98:99]
	s_add_u32 s98, s98, 0x1000
	s_addc_u32 s99, s99, 0
	global_load_dwordx4 v[72:75], v250, s[98:99]
	s_add_u32 s98, s98, 0x1000
	s_addc_u32 s99, s99, 0
	global_load_dwordx4 v[84:87], v250, s[98:99]
	s_add_u32 s98, s98, 0x1000
	s_addc_u32 s99, s99, 0
	global_load_dwordx4 v[80:83], v250, s[98:99]
	s_add_u32 s98, s98, 0x1000
	s_addc_u32 s99, s99, 0
	global_load_dwordx4 v[92:95], v250, s[98:99]
	s_add_u32 s98, s98, 0x1000
	s_addc_u32 s99, s99, 0
	global_load_dwordx4 v[88:91], v250, s[98:99]
	s_branch .Lcs3_done
.Lcs3_slow:
	s_cmp_ge_i32 s48, s44
	s_cbranch_scc0 .Lcs3_z0
	s_cmp_lt_i32 s48, s45
	s_cbranch_scc0 .Lcs3_z0
	s_lshl_b32 s49, s48, 12
	s_add_u32 s98, s28, s49
	s_addc_u32 s99, s29, 0
	global_load_dwordx4 v[52:55], v250, s[98:99]
	s_branch .Lcs3_n0
.Lcs3_z0:
	v_mov_b32_e32 v52, 0
	v_mov_b32_e32 v53, 0
	v_mov_b32_e32 v54, 0
	v_mov_b32_e32 v55, 0
.Lcs3_n0:
	s_add_i32 s48, s48, 1
	s_cmp_ge_i32 s48, s44
	s_cbranch_scc0 .Lcs3_z1
	s_cmp_lt_i32 s48, s45
	s_cbranch_scc0 .Lcs3_z1
	s_lshl_b32 s49, s48, 12
	s_add_u32 s98, s28, s49
	s_addc_u32 s99, s29, 0
	global_load_dwordx4 v[48:51], v250, s[98:99]
	s_branch .Lcs3_n1
.Lcs3_z1:
	v_mov_b32_e32 v48, 0
	v_mov_b32_e32 v49, 0
	v_mov_b32_e32 v50, 0
	v_mov_b32_e32 v51, 0
.Lcs3_n1:
	s_add_i32 s48, s48, 1
	s_cmp_ge_i32 s48, s44
	s_cbranch_scc0 .Lcs3_z2
	s_cmp_lt_i32 s48, s45
	s_cbranch_scc0 .Lcs3_z2
	s_lshl_b32 s49, s48, 12
	s_add_u32 s98, s28, s49
	s_addc_u32 s99, s29, 0
	global_load_dwordx4 v[60:63], v250, s[98:99]
	s_branch .Lcs3_n2
.Lcs3_z2:
	v_mov_b32_e32 v60, 0
	v_mov_b32_e32 v61, 0
	v_mov_b32_e32 v62, 0
	v_mov_b32_e32 v63, 0
.Lcs3_n2:
	s_add_i32 s48, s48, 1
	s_cmp_ge_i32 s48, s44
	s_cbranch_scc0 .Lcs3_z3
	s_cmp_lt_i32 s48, s45
	s_cbranch_scc0 .Lcs3_z3
	s_lshl_b32 s49, s48, 12
	s_add_u32 s98, s28, s49
	s_addc_u32 s99, s29, 0
	global_load_dwordx4 v[56:59], v250, s[98:99]
	s_branch .Lcs3_n3
.Lcs3_z3:
	v_mov_b32_e32 v56, 0
	v_mov_b32_e32 v57, 0
	v_mov_b32_e32 v58, 0
	v_mov_b32_e32 v59, 0
.Lcs3_n3:
	s_add_i32 s48, s48, 1
	s_cmp_ge_i32 s48, s44
	s_cbranch_scc0 .Lcs3_z4
	s_cmp_lt_i32 s48, s45
	s_cbranch_scc0 .Lcs3_z4
	s_lshl_b32 s49, s48, 12
	s_add_u32 s98, s28, s49
	s_addc_u32 s99, s29, 0
	global_load_dwordx4 v[68:71], v250, s[98:99]
	s_branch .Lcs3_n4
.Lcs3_z4:
	v_mov_b32_e32 v68, 0
	v_mov_b32_e32 v69, 0
	v_mov_b32_e32 v70, 0
	v_mov_b32_e32 v71, 0
.Lcs3_n4:
	s_add_i32 s48, s48, 1
	s_cmp_ge_i32 s48, s44
	s_cbranch_scc0 .Lcs3_z5
	s_cmp_lt_i32 s48, s45
	s_cbranch_scc0 .Lcs3_z5
	s_lshl_b32 s49, s48, 12
	s_add_u32 s98, s28, s49
	s_addc_u32 s99, s29, 0
	global_load_dwordx4 v[64:67], v250, s[98:99]
	s_branch .Lcs3_n5
.Lcs3_z5:
	v_mov_b32_e32 v64, 0
	v_mov_b32_e32 v65, 0
	v_mov_b32_e32 v66, 0
	v_mov_b32_e32 v67, 0
.Lcs3_n5:
	s_add_i32 s48, s48, 1
	s_cmp_ge_i32 s48, s44
	s_cbranch_scc0 .Lcs3_z6
	s_cmp_lt_i32 s48, s45
	s_cbranch_scc0 .Lcs3_z6
	s_lshl_b32 s49, s48, 12
	s_add_u32 s98, s28, s49
	s_addc_u32 s99, s29, 0
	global_load_dwordx4 v[76:79], v250, s[98:99]
	s_branch .Lcs3_n6
.Lcs3_z6:
	v_mov_b32_e32 v76, 0
	v_mov_b32_e32 v77, 0
	v_mov_b32_e32 v78, 0
	v_mov_b32_e32 v79, 0
.Lcs3_n6:
	s_add_i32 s48, s48, 1
	s_cmp_ge_i32 s48, s44
	s_cbranch_scc0 .Lcs3_z7
	s_cmp_lt_i32 s48, s45
	s_cbranch_scc0 .Lcs3_z7
	s_lshl_b32 s49, s48, 12
	s_add_u32 s98, s28, s49
	s_addc_u32 s99, s29, 0
	global_load_dwordx4 v[72:75], v250, s[98:99]
	s_branch .Lcs3_n7
.Lcs3_z7:
	v_mov_b32_e32 v72, 0
	v_mov_b32_e32 v73, 0
	v_mov_b32_e32 v74, 0
	v_mov_b32_e32 v75, 0
.Lcs3_n7:
	s_add_i32 s48, s48, 1
	s_cmp_ge_i32 s48, s44
	s_cbranch_scc0 .Lcs3_z8
	s_cmp_lt_i32 s48, s45
	s_cbranch_scc0 .Lcs3_z8
	s_lshl_b32 s49, s48, 12
	s_add_u32 s98, s28, s49
	s_addc_u32 s99, s29, 0
	global_load_dwordx4 v[84:87], v250, s[98:99]
	s_branch .Lcs3_n8
.Lcs3_z8:
	v_mov_b32_e32 v84, 0
	v_mov_b32_e32 v85, 0
	v_mov_b32_e32 v86, 0
	v_mov_b32_e32 v87, 0
.Lcs3_n8:
	s_add_i32 s48, s48, 1
	s_cmp_ge_i32 s48, s44
	s_cbranch_scc0 .Lcs3_z9
	s_cmp_lt_i32 s48, s45
	s_cbranch_scc0 .Lcs3_z9
	s_lshl_b32 s49, s48, 12
	s_add_u32 s98, s28, s49
	s_addc_u32 s99, s29, 0
	global_load_dwordx4 v[80:83], v250, s[98:99]
	s_branch .Lcs3_n9
.Lcs3_z9:
	v_mov_b32_e32 v80, 0
	v_mov_b32_e32 v81, 0
	v_mov_b32_e32 v82, 0
	v_mov_b32_e32 v83, 0
.Lcs3_n9:
	s_add_i32 s48, s48, 1
	s_cmp_ge_i32 s48, s44
	s_cbranch_scc0 .Lcs3_z10
	s_cmp_lt_i32 s48, s45
	s_cbranch_scc0 .Lcs3_z10
	s_lshl_b32 s49, s48, 12
	s_add_u32 s98, s28, s49
	s_addc_u32 s99, s29, 0
	global_load_dwordx4 v[92:95], v250, s[98:99]
	s_branch .Lcs3_n10
.Lcs3_z10:
	v_mov_b32_e32 v92, 0
	v_mov_b32_e32 v93, 0
	v_mov_b32_e32 v94, 0
	v_mov_b32_e32 v95, 0
.Lcs3_n10:
	s_add_i32 s48, s48, 1
	s_cmp_ge_i32 s48, s44
	s_cbranch_scc0 .Lcs3_z11
	s_cmp_lt_i32 s48, s45
	s_cbranch_scc0 .Lcs3_z11
	s_lshl_b32 s49, s48, 12
	s_add_u32 s98, s28, s49
	s_addc_u32 s99, s29, 0
	global_load_dwordx4 v[88:91], v250, s[98:99]
	s_branch .Lcs3_n11
.Lcs3_z11:
	v_mov_b32_e32 v88, 0
	v_mov_b32_e32 v89, 0
	v_mov_b32_e32 v90, 0
	v_mov_b32_e32 v91, 0
.Lcs3_n11:
	s_add_i32 s48, s48, 1
.Lcs3_done:
	s_mov_b64 s[0:1], exec
	s_branch .LBB0_652

.LBB0_826:
	v_or_b32_e32 v145, s0, v144
	v_subrev_u32_e32 v250, s28, v96
	v_readfirstlane_b32 s10, v145
	s_nop 0
	s_add_i32 s10, s10, s9
	s_add_i32 s11, s10, 11
	s_cmp_ge_i32 s10, s7
	s_cbranch_scc0 .Lcs5_slow
	s_cmp_lt_i32 s11, s8
	s_cbranch_scc0 .Lcs5_slow
	s_lshl_b32 s11, s10, 12
	s_add_u32 s98, s28, s11
	s_addc_u32 s99, s29, 0
	global_load_dwordx4 v[52:55], v250, s[98:99]
	s_add_u32 s98, s98, 0x1000
	s_addc_u32 s99, s99, 0
	global_load_dwordx4 v[48:51], v250, s[98:99]
	s_add_u32 s98, s98, 0x1000
	s_addc_u32 s99, s99, 0
	global_load_dwordx4 v[60:63], v250, s[98:99]
	s_add_u32 s98, s98, 0x1000
	s_addc_u32 s99, s99, 0
	global_load_dwordx4 v[56:59], v250, s[98:99]
	s_add_u32 s98, s98, 0x1000
	s_addc_u32 s99, s99, 0
	global_load_dwordx4 v[68:71], v250, s[98:99]
	s_add_u32 s98, s98, 0x1000
	s_addc_u32 s99, s99, 0
	global_load_dwordx4 v[64:67], v250, s[98:99]
	s_add_u32 s98, s98, 0x1000
	s_addc_u32 s99, s99, 0
	global_load_dwordx4 v[76:79], v250, s[98:99]
	s_add_u32 s98, s98, 0x1000
	s_addc_u32 s99, s99, 0
	global_load_dwordx4 v[72:75], v250, s[98:99]
	s_add_u32 s98, s98, 0x1000
	s_addc_u32 s99, s99, 0
	global_load_dwordx4 v[84:87], v250, s[98:99]
	s_add_u32 s98, s98, 0x1000
	s_addc_u32 s99, s99, 0
	global_load_dwordx4 v[80:83], v250, s[98:99]
	s_add_u32 s98, s98, 0x1000
	s_addc_u32 s99, s99, 0
	global_load_dwordx4 v[92:95], v250, s[98:99]
	s_add_u32 s98, s98, 0x1000
	s_addc_u32 s99, s99, 0
	global_load_dwordx4 v[88:91], v250, s[98:99]
	s_branch .Lcs5_done
.Lcs5_slow:
	s_cmp_ge_i32 s10, s7
	s_cbranch_scc0 .Lcs5_z0
	s_cmp_lt_i32 s10, s8
	s_cbranch_scc0 .Lcs5_z0
	s_lshl_b32 s11, s10, 12
	s_add_u32 s98, s28, s11
	s_addc_u32 s99, s29, 0
	global_load_dwordx4 v[52:55], v250, s[98:99]
	s_branch .Lcs5_n0

.Lcs5_n0:
	s_add_i32 s10, s10, 1
	s_cmp_ge_i32 s10, s7
	s_cbranch_scc0 .Lcs5_z1
	s_cmp_lt_i32 s10, s8
	s_cbranch_scc0 .Lcs5_z1
	s_lshl_b32 s11, s10, 12
	s_add_u32 s98, s28, s11
	s_addc_u32 s99, s29, 0
	global_load_dwordx4 v[48:51], v250, s[98:99]
	s_branch .Lcs5_n1

.Lcs5_n1:
	s_add_i32 s10, s10, 1
	s_cmp_ge_i32 s10, s7
	s_cbranch_scc0 .Lcs5_z2
	s_cmp_lt_i32 s10, s8
	s_cbranch_scc0 .Lcs5_z2
	s_lshl_b32 s11, s10, 12
	s_add_u32 s98, s28, s11
	s_addc_u32 s99, s29, 0
	global_load_dwordx4 v[60:63], v250, s[98:99]
	s_branch .Lcs5_n2

.Lcs5_n2:
	s_add_i32 s10, s10, 1
	s_cmp_ge_i32 s10, s7
	s_cbranch_scc0 .Lcs5_z3
	s_cmp_lt_i32 s10, s8
	s_cbranch_scc0 .Lcs5_z3
	s_lshl_b32 s11, s10, 12
	s_add_u32 s98, s28, s11
	s_addc_u32 s99, s29, 0
	global_load_dwordx4 v[56:59], v250, s[98:99]
	s_branch .Lcs5_n3

.Lcs5_n3:
	s_add_i32 s10, s10, 1
	s_cmp_ge_i32 s10, s7
	s_cbranch_scc0 .Lcs5_z4
	s_cmp_lt_i32 s10, s8
	s_cbranch_scc0 .Lcs5_z4
	s_lshl_b32 s11, s10, 12
	s_add_u32 s98, s28, s11
	s_addc_u32 s99, s29, 0
	global_load_dwordx4 v[68:71], v250, s[98:99]
	s_branch .Lcs5_n4

.Lcs5_n4:
	s_add_i32 s10, s10, 1
	s_cmp_ge_i32 s10, s7
	s_cbranch_scc0 .Lcs5_z5
	s_cmp_lt_i32 s10, s8
	s_cbranch_scc0 .Lcs5_z5
	s_lshl_b32 s11, s10, 12
	s_add_u32 s98, s28, s11
	s_addc_u32 s99, s29, 0
	global_load_dwordx4 v[64:67], v250, s[98:99]
	s_branch .Lcs5_n5

.Lcs5_n5:
	s_add_i32 s10, s10, 1
	s_cmp_ge_i32 s10, s7
	s_cbranch_scc0 .Lcs5_z6
	s_cmp_lt_i32 s10, s8
	s_cbranch_scc0 .Lcs5_z6
	s_lshl_b32 s11, s10, 12
	s_add_u32 s98, s28, s11
	s_addc_u32 s99, s29, 0
	global_load_dwordx4 v[76:79], v250, s[98:99]
	s_branch .Lcs5_n6

.Lcs5_n6:
	s_add_i32 s10, s10, 1
	s_cmp_ge_i32 s10, s7
	s_cbranch_scc0 .Lcs5_z7
	s_cmp_lt_i32 s10, s8
	s_cbranch_scc0 .Lcs5_z7
	s_lshl_b32 s11, s10, 12
	s_add_u32 s98, s28, s11
	s_addc_u32 s99, s29, 0
	global_load_dwordx4 v[72:75], v250, s[98:99]
	s_branch .Lcs5_n7

.Lcs5_n7:
	s_add_i32 s10, s10, 1
	s_cmp_ge_i32 s10, s7
	s_cbranch_scc0 .Lcs5_z8
	s_cmp_lt_i32 s10, s8
	s_cbranch_scc0 .Lcs5_z8
	s_lshl_b32 s11, s10, 12
	s_add_u32 s98, s28, s11
	s_addc_u32 s99, s29, 0
	global_load_dwordx4 v[84:87], v250, s[98:99]
	s_branch .Lcs5_n8

.Lcs5_n8:
	s_add_i32 s10, s10, 1
	s_cmp_ge_i32 s10, s7
	s_cbranch_scc0 .Lcs5_z9
	s_cmp_lt_i32 s10, s8
	s_cbranch_scc0 .Lcs5_z9
	s_lshl_b32 s11, s10, 12
	s_add_u32 s98, s28, s11
	s_addc_u32 s99, s29, 0
	global_load_dwordx4 v[80:83], v250, s[98:99]
	s_branch .Lcs5_n9

.Lcs5_n9:
	s_add_i32 s10, s10, 1
	s_cmp_ge_i32 s10, s7
	s_cbranch_scc0 .Lcs5_z10
	s_cmp_lt_i32 s10, s8
	s_cbranch_scc0 .Lcs5_z10
	s_lshl_b32 s11, s10, 12
	s_add_u32 s98, s28, s11
	s_addc_u32 s99, s29, 0
	global_load_dwordx4 v[92:95], v250, s[98:99]
	s_branch .Lcs5_n10

.Lcs5_n10:
	s_add_i32 s10, s10, 1
	s_cmp_ge_i32 s10, s7
	s_cbranch_scc0 .Lcs5_z11
	s_cmp_lt_i32 s10, s8
	s_cbranch_scc0 .Lcs5_z11
	s_lshl_b32 s11, s10, 12
	s_add_u32 s98, s28, s11
	s_addc_u32 s99, s29, 0
	global_load_dwordx4 v[88:91], v250, s[98:99]
	s_branch .Lcs5_n11

.Lcs5_n11:
	s_add_i32 s10, s10, 1
